# grid barrier: non-leader workgroups poll the cross-XCD release word directly (one atomic+poll hop less per barrier)
# speedup vs baseline: 1.0027x; 1.0027x over previous
; __device__ __forceinline__ unsigned xb_ld(unsigned* p)              { return __hip_atomic_load(p, __ATOMIC_RELAXED, __HIP_MEMORY_SCOPE_AGENT); }
; __device__ __forceinline__ unsigned xb_add(unsigned* p, unsigned v) { return __hip_atomic_fetch_add(p, v, __ATOMIC_RELAXED, __HIP_MEMORY_SCOPE_AGENT); }
; #define XB_SPIN(cond, bar) do { unsigned _sp = 0; while (cond) { __builtin_amdgcn_s_sleep(1); \
;     if ((++_sp & 255u) == 0u) { if (xb_ld(&(bar)[XB_TMO])) break; if (_sp > XB_SPIN_CAP) { atomicAdd(&(bar)[XB_TMO], 1u); break; } } } } while (0)
; __device__ __forceinline__ void xcd_barrier(const XcdBarrier& b) {
;     ...
;         const unsigned old = xb_add(&bar[XB_XSUB(b.x)], 1u);
;         const unsigned gen = old / nloc;
;         if (old + 1u == (gen + 1u) * nloc) {
;             __builtin_amdgcn_fence(__ATOMIC_RELEASE, "agent");
;             asm volatile("s_waitcnt vmcnt(0)" ::: "memory");
;             const unsigned og = xb_add(&bar[XB_TOP], 1u);
;             const unsigned tg = og / nx;
;             if (og + 1u == (tg + 1u) * nx) xb_add(&bar[XB_TOPGEN], 1u);
;             else XB_SPIN(xb_ld(&bar[XB_TOPGEN]) == tg, bar);
;             __builtin_amdgcn_fence(__ATOMIC_ACQUIRE, "agent");
;             xb_add(&bar[XB_XGEN(b.x)], 1u);
;             asm volatile("s_waitcnt vmcnt(0)" ::: "memory");
;         } else {
;             XB_SPIN(xb_ld(&bar[XB_XGEN(b.x)]) == gen, bar);
;             __builtin_amdgcn_fence(__ATOMIC_ACQUIRE, "agent");
;             asm volatile("s_waitcnt vmcnt(0)" ::: "memory");
;         }
.LBB0_1953:
	s_mov_b64 s[4:5], exec
	v_mbcnt_lo_u32_b32 v1, s4, 0
	v_mbcnt_hi_u32_b32 v1, s5, v1
	v_cmp_eq_u32_e32 vcc, 0, v1
	s_and_saveexec_b64 s[2:3], vcc
	s_cbranch_execz .LBB0_1955
	s_bcnt1_i32_b64 s4, s[4:5]
	v_mov_b32_e32 v3, s4
	v_readlane_b32 s4, v251, 3
	v_readlane_b32 s5, v251, 4
	s_nop 4
	global_load_dword v16, v129, s[4:5] sc1
	v_readlane_b32 s4, v250, 61
	v_readlane_b32 s5, v250, 62
	s_nop 4
	global_atomic_add v3, v129, v3, s[4:5] sc0
.LBB0_1955:
	s_or_b64 exec, exec, s[2:3]
	v_cvt_f32_u32_e32 v4, v2
	s_waitcnt vmcnt(0)
	v_readfirstlane_b32 s2, v3
	v_sub_u32_e32 v3, 0, v2
	v_rcp_iflag_f32_e32 v4, v4
	v_add_u32_e32 v5, s2, v1
	v_mul_f32_e32 v4, 0x4f7ffffe, v4
	v_cvt_u32_f32_e32 v4, v4
	v_mul_lo_u32 v1, v3, v4
	v_mul_hi_u32 v1, v4, v1
	v_add_u32_e32 v1, v4, v1
	v_mul_hi_u32 v1, v5, v1
	v_mul_lo_u32 v3, v1, v2
	v_sub_u32_e32 v3, v5, v3
	v_add_u32_e32 v4, 1, v1
	v_cmp_ge_u32_e32 vcc, v3, v2
	s_nop 1
	v_cndmask_b32_e32 v1, v1, v4, vcc
	v_sub_u32_e32 v4, v3, v2
	v_cndmask_b32_e32 v3, v3, v4, vcc
	v_add_u32_e32 v4, 1, v1
	v_cmp_ge_u32_e32 vcc, v3, v2
	v_add_u32_e32 v3, 1, v5
	s_nop 0
	v_cndmask_b32_e32 v1, v1, v4, vcc
	v_mul_lo_u32 v4, v2, v1
	v_add_u32_e32 v2, v4, v2
	v_cmp_ne_u32_e32 vcc, v3, v2
	s_and_saveexec_b64 s[2:3], vcc
	s_xor_b64 s[2:3], exec, s[2:3]
	s_cbranch_execz .LBB0_1969
	v_readlane_b32 s4, v251, 3
	v_readlane_b32 s5, v251, 4
	s_waitcnt lgkmcnt(0)
	s_nop 3
	global_load_dword v0, v129, s[4:5] sc1
	s_waitcnt vmcnt(0)
	v_cmp_eq_u32_e32 vcc, v0, v16
	s_and_saveexec_b64 s[4:5], vcc
	s_cbranch_execz .LBB0_1968
	s_mov_b32 s18, 1
	s_mov_b64 s[6:7], 0
	s_branch .LBB0_1959

; __device__ __forceinline__ unsigned xb_ld(unsigned* p)              { return __hip_atomic_load(p, __ATOMIC_RELAXED, __HIP_MEMORY_SCOPE_AGENT); }
; #define XB_SPIN(cond, bar) do { unsigned _sp = 0; while (cond) { __builtin_amdgcn_s_sleep(1); \
;     if ((++_sp & 255u) == 0u) { if (xb_ld(&(bar)[XB_TMO])) break; if (_sp > XB_SPIN_CAP) { atomicAdd(&(bar)[XB_TMO], 1u); break; } } } } while (0)
; __device__ __forceinline__ void xcd_barrier(const XcdBarrier& b) {
;     ...
;             XB_SPIN(xb_ld(&bar[XB_XGEN(b.x)]) == gen, bar);
.LBB0_1961:
	v_readlane_b32 s12, v251, 3
	v_readlane_b32 s13, v251, 4
	s_add_i32 s18, s18, 1
	s_mov_b64 s[14:15], -1
	s_nop 2
	global_load_dword v0, v129, s[12:13] sc1
	s_waitcnt vmcnt(0)
	v_cmp_ne_u32_e32 vcc, v0, v16
	s_orn2_b64 s[12:13], vcc, exec
	s_branch .LBB0_1958

; __device__ __forceinline__ unsigned xb_ld(unsigned* p)              { return __hip_atomic_load(p, __ATOMIC_RELAXED, __HIP_MEMORY_SCOPE_AGENT); }
; __device__ __forceinline__ unsigned xb_add(unsigned* p, unsigned v) { return __hip_atomic_fetch_add(p, v, __ATOMIC_RELAXED, __HIP_MEMORY_SCOPE_AGENT); }
; #define XB_SPIN(cond, bar) do { unsigned _sp = 0; while (cond) { __builtin_amdgcn_s_sleep(1); \
;     if ((++_sp & 255u) == 0u) { if (xb_ld(&(bar)[XB_TMO])) break; if (_sp > XB_SPIN_CAP) { atomicAdd(&(bar)[XB_TMO], 1u); break; } } } } while (0)
; __device__ __forceinline__ void xcd_barrier(const XcdBarrier& b) {
;     ...
;         const unsigned old = xb_add(&bar[XB_XSUB(b.x)], 1u);
;         const unsigned gen = old / nloc;
;         if (old + 1u == (gen + 1u) * nloc) {
;             __builtin_amdgcn_fence(__ATOMIC_RELEASE, "agent");
;             asm volatile("s_waitcnt vmcnt(0)" ::: "memory");
;             const unsigned og = xb_add(&bar[XB_TOP], 1u);
;             const unsigned tg = og / nx;
;             if (og + 1u == (tg + 1u) * nx) xb_add(&bar[XB_TOPGEN], 1u);
;             else XB_SPIN(xb_ld(&bar[XB_TOPGEN]) == tg, bar);
;             __builtin_amdgcn_fence(__ATOMIC_ACQUIRE, "agent");
;             xb_add(&bar[XB_XGEN(b.x)], 1u);
;             asm volatile("s_waitcnt vmcnt(0)" ::: "memory");
;         } else {
;             XB_SPIN(xb_ld(&bar[XB_XGEN(b.x)]) == gen, bar);
;             __builtin_amdgcn_fence(__ATOMIC_ACQUIRE, "agent");
;             asm volatile("s_waitcnt vmcnt(0)" ::: "memory");
;         }
.LBB0_4452:
	s_or_b64 exec, exec, s[2:3]
	v_cvt_f32_u32_e32 v4, v2
	s_waitcnt vmcnt(0)
	v_readfirstlane_b32 s2, v3
	v_sub_u32_e32 v3, 0, v2
	v_rcp_iflag_f32_e32 v4, v4
	v_add_u32_e32 v5, s2, v1
	v_mul_f32_e32 v4, 0x4f7ffffe, v4
	v_cvt_u32_f32_e32 v4, v4
	v_mul_lo_u32 v1, v3, v4
	v_mul_hi_u32 v1, v4, v1
	v_add_u32_e32 v1, v4, v1
	v_mul_hi_u32 v1, v5, v1
	v_mul_lo_u32 v3, v1, v2
	v_sub_u32_e32 v3, v5, v3
	v_add_u32_e32 v4, 1, v1
	v_cmp_ge_u32_e32 vcc, v3, v2
	s_nop 1
	v_cndmask_b32_e32 v1, v1, v4, vcc
	v_sub_u32_e32 v4, v3, v2
	v_cndmask_b32_e32 v3, v3, v4, vcc
	v_add_u32_e32 v4, 1, v1
	v_cmp_ge_u32_e32 vcc, v3, v2
	v_add_u32_e32 v3, 1, v5
	s_nop 0
	v_cndmask_b32_e32 v1, v1, v4, vcc
	v_mul_lo_u32 v4, v2, v1
	v_add_u32_e32 v2, v4, v2
	v_cmp_ne_u32_e32 vcc, v3, v2
	s_and_saveexec_b64 s[2:3], vcc
	s_xor_b64 s[2:3], exec, s[2:3]
	s_cbranch_execz .LBB0_4466
	v_readlane_b32 s4, v251, 3
	v_readlane_b32 s5, v251, 4
	s_waitcnt lgkmcnt(0)
	s_nop 3
	global_load_dword v0, v129, s[4:5] sc1
	s_waitcnt vmcnt(0)
	v_cmp_eq_u32_e32 vcc, v0, v16
	s_and_saveexec_b64 s[4:5], vcc
	s_cbranch_execz .LBB0_4465
	s_mov_b32 s16, 1
	s_mov_b64 s[6:7], 0
	s_branch .LBB0_4456

; __device__ __forceinline__ unsigned xb_ld(unsigned* p)              { return __hip_atomic_load(p, __ATOMIC_RELAXED, __HIP_MEMORY_SCOPE_AGENT); }
; #define XB_SPIN(cond, bar) do { unsigned _sp = 0; while (cond) { __builtin_amdgcn_s_sleep(1); \
;     if ((++_sp & 255u) == 0u) { if (xb_ld(&(bar)[XB_TMO])) break; if (_sp > XB_SPIN_CAP) { atomicAdd(&(bar)[XB_TMO], 1u); break; } } } } while (0)
; __device__ __forceinline__ void xcd_barrier(const XcdBarrier& b) {
;     ...
;             XB_SPIN(xb_ld(&bar[XB_XGEN(b.x)]) == gen, bar);
.LBB0_4458:
	v_readlane_b32 s10, v251, 3
	v_readlane_b32 s11, v251, 4
	s_add_i32 s16, s16, 1
	s_mov_b64 s[12:13], -1
	s_nop 2
	global_load_dword v0, v129, s[10:11] sc1
	s_waitcnt vmcnt(0)
	v_cmp_ne_u32_e32 vcc, v0, v16
	s_orn2_b64 s[10:11], vcc, exec
	s_branch .LBB0_4455
